# phase13 compression k-loop: two-deep register prefetch (unrolled x2)
# speedup vs baseline: 1.0549x; 1.0019x over previous
; template <class ARowF>
; __device__ __forceinline__ void gemm_mainloop(f32x4 (&acc)[4][4], ARowF arow, int a_kstep, const u16* bt, int ldb, int nk, u16* sm) {
;     ...
;   for (int kt = 0; kt < nk; ++kt) {
;     const bool more = (kt + 1 < nk);
;     if (more) {
; #pragma unroll
;       for (int i = 0; i < 4; ++i) ra[i] = *(const uint4*)(pa[i] + (size_t)(kt + 1) * a_kstep);
; #pragma unroll
;       for (int i = 0; i < 2; ++i) rb[i] = *(const uint4*)(pb[i] + (size_t)(kt + 1) * 64);
;     }
;     const u16* cA = sA + (kt & 1) * 256 * LDSP + (wm * 64 + fr) * LDSP + fq * 8;
;     const u16* cB = sB + (kt & 1) * 128 * LDSP + (wn * 64 + fr) * LDSP + fq * 8;
; #pragma unroll
;     for (int ks = 0; ks < 2; ++ks) {
;       bf16x8 wf[4], xf[4];
; #pragma unroll
;       for (int i = 0; i < 4; ++i) {
;         wf[i] = *(const bf16x8*)(cB + i * 16 * LDSP + ks * 32);
;         xf[i] = *(const bf16x8*)(cA + i * 16 * LDSP + ks * 32);
;       }
; #pragma unroll
;       for (int i = 0; i < 4; ++i)
; #pragma unroll
;         for (int j = 0; j < 4; ++j) acc[i][j] = mfma16(wf[i], xf[j], acc[i][j]);
;     }
;     if (more) {
;       u16* dA = sA + ((kt + 1) & 1) * 256 * LDSP; u16* dB = sB + ((kt + 1) & 1) * 128 * LDSP;
; #pragma unroll
;       for (int i = 0; i < 4; ++i) *(uint4*)(dA + (lr + 64 * i) * LDSP + lc * 8) = ra[i];
; #pragma unroll
;       for (int i = 0; i < 2; ++i) *(uint4*)(dB + (lr + 64 * i) * LDSP + lc * 8) = rb[i];
;     }
;     __syncthreads();
;   }
.LBB0_896:
	v_lshl_add_u64 v[174:175], v[66:67], 0, v[196:197]
	v_lshl_add_u64 v[176:177], v[68:69], 0, v[196:197]
	v_lshl_add_u64 v[178:179], v[70:71], 0, v[196:197]
	v_lshl_add_u64 v[180:181], v[72:73], 0, v[196:197]
	v_lshl_add_u64 v[182:183], v[64:65], 0, v[196:197]
	global_load_dwordx4 v[150:153], v[174:175], off
	global_load_dwordx4 v[154:157], v[176:177], off
	global_load_dwordx4 v[158:161], v[178:179], off
	global_load_dwordx4 v[162:165], v[180:181], off
	global_load_dwordx4 v[166:169], v[182:183], off offset:128
	v_add_co_u32_e32 v182, vcc, s31, v182
	v_lshl_add_u64 v[66:67], v[66:67], 0, s[24:25]
	v_lshl_add_u64 v[68:69], v[68:69], 0, s[24:25]
	v_addc_co_u32_e32 v183, vcc, 0, v183, vcc
	global_load_dwordx4 v[170:173], v[182:183], off offset:128
	v_lshl_add_u64 v[70:71], v[70:71], 0, s[24:25]
	v_lshl_add_u64 v[72:73], v[72:73], 0, s[24:25]
	v_lshl_add_u64 v[64:65], v[64:65], 0, s[22:23]
	s_mov_b32 s8, 0
.Lc13_loop:
	v_lshl_add_u64 v[174:175], v[66:67], 0, v[196:197]
	v_lshl_add_u64 v[176:177], v[68:69], 0, v[196:197]
	v_lshl_add_u64 v[178:179], v[70:71], 0, v[196:197]
	v_lshl_add_u64 v[180:181], v[72:73], 0, v[196:197]
	v_lshl_add_u64 v[182:183], v[64:65], 0, v[196:197]
	global_load_dwordx4 v[126:129], v[174:175], off
	global_load_dwordx4 v[130:133], v[176:177], off
	global_load_dwordx4 v[134:137], v[178:179], off
	global_load_dwordx4 v[138:141], v[180:181], off
	global_load_dwordx4 v[142:145], v[182:183], off offset:128
	v_add_co_u32_e32 v182, vcc, s31, v182
	v_lshl_add_u64 v[66:67], v[66:67], 0, s[24:25]
	v_lshl_add_u64 v[68:69], v[68:69], 0, s[24:25]
	v_addc_co_u32_e32 v183, vcc, 0, v183, vcc
	global_load_dwordx4 v[146:149], v[182:183], off offset:128
	v_lshl_add_u64 v[70:71], v[70:71], 0, s[24:25]
	v_lshl_add_u64 v[72:73], v[72:73], 0, s[24:25]
	v_lshl_add_u64 v[64:65], v[64:65], 0, s[22:23]
	ds_read_b128 v[74:77], v238
	ds_read_b128 v[78:81], v237
	ds_read_b128 v[82:85], v238 offset:64
	ds_read_b128 v[86:89], v237 offset:64
	ds_read_b128 v[90:93], v237 offset:2304
	ds_read_b128 v[94:97], v237 offset:2368
	ds_read_b128 v[98:101], v237 offset:4608
	ds_read_b128 v[102:105], v237 offset:4672
	ds_read_b128 v[106:109], v237 offset:6912
	ds_read_b128 v[110:113], v237 offset:6976
	s_waitcnt lgkmcnt(8)
	v_mfma_f32_16x16x32_bf16 v[44:47], v[74:77], v[78:81], v[44:47]
	s_waitcnt lgkmcnt(5)
	v_mfma_f32_16x16x32_bf16 v[40:43], v[74:77], v[90:93], v[40:43]
	s_waitcnt lgkmcnt(3)
	v_mfma_f32_16x16x32_bf16 v[36:39], v[74:77], v[98:101], v[36:39]
	s_waitcnt lgkmcnt(1)
	v_mfma_f32_16x16x32_bf16 v[32:35], v[74:77], v[106:109], v[32:35]
	ds_read_b128 v[74:77], v238 offset:2304
	ds_read_b128 v[114:117], v238 offset:2368
	s_waitcnt lgkmcnt(1)
	v_mfma_f32_16x16x32_bf16 v[28:31], v[74:77], v[78:81], v[28:31]
	v_mfma_f32_16x16x32_bf16 v[8:11], v[74:77], v[90:93], v[8:11]
	v_mfma_f32_16x16x32_bf16 v[4:7], v[74:77], v[98:101], v[4:7]
	v_mfma_f32_16x16x32_bf16 v[0:3], v[74:77], v[106:109], v[0:3]
	ds_read_b128 v[74:77], v238 offset:4608
	ds_read_b128 v[118:121], v238 offset:4672
	s_waitcnt lgkmcnt(1)
	v_mfma_f32_16x16x32_bf16 v[16:19], v[74:77], v[78:81], v[16:19]
	v_mfma_f32_16x16x32_bf16 v[24:27], v[74:77], v[90:93], v[24:27]
	v_mfma_f32_16x16x32_bf16 v[20:23], v[74:77], v[98:101], v[20:23]
	v_mfma_f32_16x16x32_bf16 v[12:15], v[74:77], v[106:109], v[12:15]
	ds_read_b128 v[74:77], v238 offset:6912
	ds_read_b128 v[122:125], v238 offset:6976
	s_waitcnt lgkmcnt(1)
	v_mfma_f32_16x16x32_bf16 v[56:59], v[74:77], v[78:81], v[56:59]
	v_mfma_f32_16x16x32_bf16 v[48:51], v[74:77], v[90:93], v[48:51]
	v_mfma_f32_16x16x32_bf16 v[60:63], v[74:77], v[98:101], v[60:63]
	v_mfma_f32_16x16x32_bf16 v[52:55], v[74:77], v[106:109], v[52:55]
	v_mfma_f32_16x16x32_bf16 v[44:47], v[82:85], v[86:89], v[44:47]
	v_mfma_f32_16x16x32_bf16 v[40:43], v[82:85], v[94:97], v[40:43]
	v_mfma_f32_16x16x32_bf16 v[36:39], v[82:85], v[102:105], v[36:39]
	v_mfma_f32_16x16x32_bf16 v[32:35], v[82:85], v[110:113], v[32:35]
	v_mfma_f32_16x16x32_bf16 v[28:31], v[114:117], v[86:89], v[28:31]
	v_mfma_f32_16x16x32_bf16 v[8:11], v[114:117], v[94:97], v[8:11]
	v_mfma_f32_16x16x32_bf16 v[4:7], v[114:117], v[102:105], v[4:7]
	v_mfma_f32_16x16x32_bf16 v[0:3], v[114:117], v[110:113], v[0:3]
	v_mfma_f32_16x16x32_bf16 v[16:19], v[118:121], v[86:89], v[16:19]
	v_mfma_f32_16x16x32_bf16 v[24:27], v[118:121], v[94:97], v[24:27]
	v_mfma_f32_16x16x32_bf16 v[20:23], v[118:121], v[102:105], v[20:23]
	v_mfma_f32_16x16x32_bf16 v[12:15], v[118:121], v[110:113], v[12:15]
	s_waitcnt lgkmcnt(0)
	v_mfma_f32_16x16x32_bf16 v[56:59], v[122:125], v[86:89], v[56:59]
	s_waitcnt vmcnt(6)
	ds_write_b128 v231, v[150:153] offset:36864
	ds_write_b128 v231, v[154:157] offset:46080
	ds_write_b128 v231, v[158:161] offset:55296
	ds_write_b128 v231, v[162:165] offset:64512
	ds_write_b128 v235, v[166:169] offset:18432
	ds_write_b128 v235, v[170:173] offset:27648
	v_mfma_f32_16x16x32_bf16 v[48:51], v[122:125], v[94:97], v[48:51]
	s_waitcnt lgkmcnt(0)
	s_barrier
; template <class ARowF>
; __device__ __forceinline__ void gemm_mainloop(f32x4 (&acc)[4][4], ARowF arow, int a_kstep, const u16* bt, int ldb, int nk, u16* sm) {
;     ...
;   for (int kt = 0; kt < nk; ++kt) {
;     const bool more = (kt + 1 < nk);
;     if (more) {
; #pragma unroll
;       for (int i = 0; i < 4; ++i) ra[i] = *(const uint4*)(pa[i] + (size_t)(kt + 1) * a_kstep);
; #pragma unroll
;       for (int i = 0; i < 2; ++i) rb[i] = *(const uint4*)(pb[i] + (size_t)(kt + 1) * 64);
;     }
;     const u16* cA = sA + (kt & 1) * 256 * LDSP + (wm * 64 + fr) * LDSP + fq * 8;
;     const u16* cB = sB + (kt & 1) * 128 * LDSP + (wn * 64 + fr) * LDSP + fq * 8;
; #pragma unroll
;     for (int ks = 0; ks < 2; ++ks) {
;       bf16x8 wf[4], xf[4];
; #pragma unroll
;       for (int i = 0; i < 4; ++i) {
;         wf[i] = *(const bf16x8*)(cB + i * 16 * LDSP + ks * 32);
;         xf[i] = *(const bf16x8*)(cA + i * 16 * LDSP + ks * 32);
;       }
; #pragma unroll
;       for (int i = 0; i < 4; ++i)
; #pragma unroll
;         for (int j = 0; j < 4; ++j) acc[i][j] = mfma16(wf[i], xf[j], acc[i][j]);
;     }
;     if (more) {
;       u16* dA = sA + ((kt + 1) & 1) * 256 * LDSP; u16* dB = sB + ((kt + 1) & 1) * 128 * LDSP;
; #pragma unroll
;       for (int i = 0; i < 4; ++i) *(uint4*)(dA + (lr + 64 * i) * LDSP + lc * 8) = ra[i];
; #pragma unroll
;       for (int i = 0; i < 2; ++i) *(uint4*)(dB + (lr + 64 * i) * LDSP + lc * 8) = rb[i];
;     }
;     __syncthreads();
;   }
	v_mfma_f32_16x16x32_bf16 v[60:63], v[122:125], v[102:105], v[60:63]
	v_mfma_f32_16x16x32_bf16 v[52:55], v[122:125], v[110:113], v[52:55]
	v_lshl_add_u64 v[174:175], v[66:67], 0, v[196:197]
	v_lshl_add_u64 v[176:177], v[68:69], 0, v[196:197]
	v_lshl_add_u64 v[178:179], v[70:71], 0, v[196:197]
	v_lshl_add_u64 v[180:181], v[72:73], 0, v[196:197]
	v_lshl_add_u64 v[182:183], v[64:65], 0, v[196:197]
	global_load_dwordx4 v[150:153], v[174:175], off
	global_load_dwordx4 v[154:157], v[176:177], off
	global_load_dwordx4 v[158:161], v[178:179], off
	global_load_dwordx4 v[162:165], v[180:181], off
	global_load_dwordx4 v[166:169], v[182:183], off offset:128
	v_add_co_u32_e32 v182, vcc, s31, v182
	v_lshl_add_u64 v[66:67], v[66:67], 0, s[24:25]
	v_lshl_add_u64 v[68:69], v[68:69], 0, s[24:25]
	v_addc_co_u32_e32 v183, vcc, 0, v183, vcc
	global_load_dwordx4 v[170:173], v[182:183], off offset:128
	v_lshl_add_u64 v[70:71], v[70:71], 0, s[24:25]
	v_lshl_add_u64 v[72:73], v[72:73], 0, s[24:25]
	v_lshl_add_u64 v[64:65], v[64:65], 0, s[22:23]
	ds_read_b128 v[74:77], v238 offset:18432
	ds_read_b128 v[78:81], v237 offset:36864
	ds_read_b128 v[82:85], v238 offset:18496
	ds_read_b128 v[86:89], v237 offset:36928
	ds_read_b128 v[90:93], v237 offset:39168
	ds_read_b128 v[94:97], v237 offset:39232
	ds_read_b128 v[98:101], v237 offset:41472
	ds_read_b128 v[102:105], v237 offset:41536
	ds_read_b128 v[106:109], v237 offset:43776
	ds_read_b128 v[110:113], v237 offset:43840
	s_waitcnt lgkmcnt(8)
	v_mfma_f32_16x16x32_bf16 v[44:47], v[74:77], v[78:81], v[44:47]
	s_waitcnt lgkmcnt(5)
	v_mfma_f32_16x16x32_bf16 v[40:43], v[74:77], v[90:93], v[40:43]
	s_waitcnt lgkmcnt(3)
	v_mfma_f32_16x16x32_bf16 v[36:39], v[74:77], v[98:101], v[36:39]
	s_waitcnt lgkmcnt(1)
	v_mfma_f32_16x16x32_bf16 v[32:35], v[74:77], v[106:109], v[32:35]
	ds_read_b128 v[74:77], v238 offset:20736
	ds_read_b128 v[114:117], v238 offset:20800
	s_waitcnt lgkmcnt(1)
	v_mfma_f32_16x16x32_bf16 v[28:31], v[74:77], v[78:81], v[28:31]
	v_mfma_f32_16x16x32_bf16 v[8:11], v[74:77], v[90:93], v[8:11]
	v_mfma_f32_16x16x32_bf16 v[4:7], v[74:77], v[98:101], v[4:7]
	v_mfma_f32_16x16x32_bf16 v[0:3], v[74:77], v[106:109], v[0:3]
	ds_read_b128 v[74:77], v238 offset:23040
	ds_read_b128 v[118:121], v238 offset:23104
	s_waitcnt lgkmcnt(1)
	v_mfma_f32_16x16x32_bf16 v[16:19], v[74:77], v[78:81], v[16:19]
	v_mfma_f32_16x16x32_bf16 v[24:27], v[74:77], v[90:93], v[24:27]
	v_mfma_f32_16x16x32_bf16 v[20:23], v[74:77], v[98:101], v[20:23]
	v_mfma_f32_16x16x32_bf16 v[12:15], v[74:77], v[106:109], v[12:15]
	ds_read_b128 v[74:77], v238 offset:25344
	ds_read_b128 v[122:125], v238 offset:25408
	s_waitcnt lgkmcnt(1)
	v_mfma_f32_16x16x32_bf16 v[56:59], v[74:77], v[78:81], v[56:59]
	v_mfma_f32_16x16x32_bf16 v[48:51], v[74:77], v[90:93], v[48:51]
	v_mfma_f32_16x16x32_bf16 v[60:63], v[74:77], v[98:101], v[60:63]
	v_mfma_f32_16x16x32_bf16 v[52:55], v[74:77], v[106:109], v[52:55]
	v_mfma_f32_16x16x32_bf16 v[44:47], v[82:85], v[86:89], v[44:47]
	v_mfma_f32_16x16x32_bf16 v[40:43], v[82:85], v[94:97], v[40:43]
	v_mfma_f32_16x16x32_bf16 v[36:39], v[82:85], v[102:105], v[36:39]
	v_mfma_f32_16x16x32_bf16 v[32:35], v[82:85], v[110:113], v[32:35]
	v_mfma_f32_16x16x32_bf16 v[28:31], v[114:117], v[86:89], v[28:31]
	v_mfma_f32_16x16x32_bf16 v[8:11], v[114:117], v[94:97], v[8:11]
	v_mfma_f32_16x16x32_bf16 v[4:7], v[114:117], v[102:105], v[4:7]
	v_mfma_f32_16x16x32_bf16 v[0:3], v[114:117], v[110:113], v[0:3]
	v_mfma_f32_16x16x32_bf16 v[16:19], v[118:121], v[86:89], v[16:19]
	v_mfma_f32_16x16x32_bf16 v[24:27], v[118:121], v[94:97], v[24:27]
	v_mfma_f32_16x16x32_bf16 v[20:23], v[118:121], v[102:105], v[20:23]
	v_mfma_f32_16x16x32_bf16 v[12:15], v[118:121], v[110:113], v[12:15]
	s_waitcnt lgkmcnt(0)
	v_mfma_f32_16x16x32_bf16 v[56:59], v[122:125], v[86:89], v[56:59]
	s_waitcnt vmcnt(6)
	ds_write_b128 v231, v[126:129]
	ds_write_b128 v231, v[130:133] offset:9216
	ds_write_b128 v231, v[134:137] offset:18432
	ds_write_b128 v231, v[138:141] offset:27648
	ds_write_b128 v235, v[142:145]
	ds_write_b128 v235, v[146:149] offset:9216
	v_mfma_f32_16x16x32_bf16 v[48:51], v[122:125], v[94:97], v[48:51]
	s_waitcnt lgkmcnt(0)
	s_barrier
	v_mfma_f32_16x16x32_bf16 v[60:63], v[122:125], v[102:105], v[60:63]
	v_mfma_f32_16x16x32_bf16 v[52:55], v[122:125], v[110:113], v[52:55]
	s_add_i32 s8, s8, 2
	s_cmp_lt_u32 s8, 30
	s_cbranch_scc1 .Lc13_loop
; template <class ARowF>
; __device__ __forceinline__ void gemm_mainloop(f32x4 (&acc)[4][4], ARowF arow, int a_kstep, const u16* bt, int ldb, int nk, u16* sm) {
;     ...
;   for (int kt = 0; kt < nk; ++kt) {
;     const bool more = (kt + 1 < nk);
;     if (more) {
; #pragma unroll
;       for (int i = 0; i < 4; ++i) ra[i] = *(const uint4*)(pa[i] + (size_t)(kt + 1) * a_kstep);
; #pragma unroll
;       for (int i = 0; i < 2; ++i) rb[i] = *(const uint4*)(pb[i] + (size_t)(kt + 1) * 64);
;     }
;     const u16* cA = sA + (kt & 1) * 256 * LDSP + (wm * 64 + fr) * LDSP + fq * 8;
;     const u16* cB = sB + (kt & 1) * 128 * LDSP + (wn * 64 + fr) * LDSP + fq * 8;
; #pragma unroll
;     for (int ks = 0; ks < 2; ++ks) {
;       bf16x8 wf[4], xf[4];
; #pragma unroll
;       for (int i = 0; i < 4; ++i) {
;         wf[i] = *(const bf16x8*)(cB + i * 16 * LDSP + ks * 32);
;         xf[i] = *(const bf16x8*)(cA + i * 16 * LDSP + ks * 32);
;       }
; #pragma unroll
;       for (int i = 0; i < 4; ++i)
; #pragma unroll
;         for (int j = 0; j < 4; ++j) acc[i][j] = mfma16(wf[i], xf[j], acc[i][j]);
;     }
;     if (more) {
;       u16* dA = sA + ((kt + 1) & 1) * 256 * LDSP; u16* dB = sB + ((kt + 1) & 1) * 128 * LDSP;
; #pragma unroll
;       for (int i = 0; i < 4; ++i) *(uint4*)(dA + (lr + 64 * i) * LDSP + lc * 8) = ra[i];
; #pragma unroll
;       for (int i = 0; i < 2; ++i) *(uint4*)(dB + (lr + 64 * i) * LDSP + lc * 8) = rb[i];
;     }
;     __syncthreads();
;   }
; __device__ __forceinline__ void phase_compress(const Params& p, u16* sm) {
;     ...
; #pragma unroll
;     for (int i = 0; i < 4; ++i) {
;       const int n = wn * 64 + i * 16 + fq * 4;
;       float bb[4] = {0.f, 0.f, 0.f, 0.f};
; #pragma unroll
;       for (int c8 = 0; c8 < 32; ++c8) {
;         const float4 bv = *(const float4*)(bias + c8 * 128 + n);
;         bb[0] += bv.x; bb[1] += bv.y; bb[2] += bv.z; bb[3] += bv.w;
;       }
	ds_read_b128 v[74:77], v238
	ds_read_b128 v[78:81], v237
	ds_read_b128 v[82:85], v238 offset:64
	ds_read_b128 v[86:89], v237 offset:64
	ds_read_b128 v[90:93], v237 offset:2304
	ds_read_b128 v[94:97], v237 offset:2368
	ds_read_b128 v[98:101], v237 offset:4608
	ds_read_b128 v[102:105], v237 offset:4672
	ds_read_b128 v[106:109], v237 offset:6912
	ds_read_b128 v[110:113], v237 offset:6976
	s_waitcnt lgkmcnt(8)
	v_mfma_f32_16x16x32_bf16 v[44:47], v[74:77], v[78:81], v[44:47]
	s_waitcnt lgkmcnt(5)
	v_mfma_f32_16x16x32_bf16 v[40:43], v[74:77], v[90:93], v[40:43]
	s_waitcnt lgkmcnt(3)
	v_mfma_f32_16x16x32_bf16 v[36:39], v[74:77], v[98:101], v[36:39]
	s_waitcnt lgkmcnt(1)
	v_mfma_f32_16x16x32_bf16 v[32:35], v[74:77], v[106:109], v[32:35]
	ds_read_b128 v[74:77], v238 offset:2304
	ds_read_b128 v[114:117], v238 offset:2368
	s_waitcnt lgkmcnt(1)
	v_mfma_f32_16x16x32_bf16 v[28:31], v[74:77], v[78:81], v[28:31]
	v_mfma_f32_16x16x32_bf16 v[8:11], v[74:77], v[90:93], v[8:11]
	v_mfma_f32_16x16x32_bf16 v[4:7], v[74:77], v[98:101], v[4:7]
	v_mfma_f32_16x16x32_bf16 v[0:3], v[74:77], v[106:109], v[0:3]
	ds_read_b128 v[74:77], v238 offset:4608
	ds_read_b128 v[118:121], v238 offset:4672
	s_waitcnt lgkmcnt(1)
	v_mfma_f32_16x16x32_bf16 v[16:19], v[74:77], v[78:81], v[16:19]
	v_mfma_f32_16x16x32_bf16 v[24:27], v[74:77], v[90:93], v[24:27]
	v_mfma_f32_16x16x32_bf16 v[20:23], v[74:77], v[98:101], v[20:23]
	v_mfma_f32_16x16x32_bf16 v[12:15], v[74:77], v[106:109], v[12:15]
	ds_read_b128 v[74:77], v238 offset:6912
	ds_read_b128 v[122:125], v238 offset:6976
	s_waitcnt lgkmcnt(1)
	v_mfma_f32_16x16x32_bf16 v[56:59], v[74:77], v[78:81], v[56:59]
	v_mfma_f32_16x16x32_bf16 v[48:51], v[74:77], v[90:93], v[48:51]
	v_mfma_f32_16x16x32_bf16 v[60:63], v[74:77], v[98:101], v[60:63]
	v_mfma_f32_16x16x32_bf16 v[52:55], v[74:77], v[106:109], v[52:55]
	v_mfma_f32_16x16x32_bf16 v[44:47], v[82:85], v[86:89], v[44:47]
	v_mfma_f32_16x16x32_bf16 v[40:43], v[82:85], v[94:97], v[40:43]
	v_mfma_f32_16x16x32_bf16 v[36:39], v[82:85], v[102:105], v[36:39]
	v_mfma_f32_16x16x32_bf16 v[32:35], v[82:85], v[110:113], v[32:35]
	v_mfma_f32_16x16x32_bf16 v[28:31], v[114:117], v[86:89], v[28:31]
	v_mfma_f32_16x16x32_bf16 v[8:11], v[114:117], v[94:97], v[8:11]
	v_mfma_f32_16x16x32_bf16 v[4:7], v[114:117], v[102:105], v[4:7]
	v_mfma_f32_16x16x32_bf16 v[0:3], v[114:117], v[110:113], v[0:3]
	v_mfma_f32_16x16x32_bf16 v[16:19], v[118:121], v[86:89], v[16:19]
	v_mfma_f32_16x16x32_bf16 v[24:27], v[118:121], v[94:97], v[24:27]
	v_mfma_f32_16x16x32_bf16 v[20:23], v[118:121], v[102:105], v[20:23]
	v_mfma_f32_16x16x32_bf16 v[12:15], v[118:121], v[110:113], v[12:15]
	s_waitcnt lgkmcnt(0)
	v_mfma_f32_16x16x32_bf16 v[56:59], v[122:125], v[86:89], v[56:59]
	s_waitcnt vmcnt(0)
	ds_write_b128 v231, v[150:153] offset:36864
	ds_write_b128 v231, v[154:157] offset:46080
	ds_write_b128 v231, v[158:161] offset:55296
	ds_write_b128 v231, v[162:165] offset:64512
	ds_write_b128 v235, v[166:169] offset:18432
	ds_write_b128 v235, v[170:173] offset:27648
	v_mfma_f32_16x16x32_bf16 v[48:51], v[122:125], v[94:97], v[48:51]
	s_waitcnt lgkmcnt(0)
	s_barrier
	v_mfma_f32_16x16x32_bf16 v[60:63], v[122:125], v[102:105], v[60:63]
	v_mfma_f32_16x16x32_bf16 v[52:55], v[122:125], v[110:113], v[52:55]
	s_mov_b32 s8, 31
	ds_read_b128 v[64:67], v238 offset:18432
	ds_read_b128 v[68:71], v237 offset:36864
	ds_read_b128 v[72:75], v238 offset:20736
	ds_read_b128 v[76:79], v237 offset:39168
	ds_read_b128 v[80:83], v238 offset:23040
	ds_read_b128 v[84:87], v237 offset:41472
	ds_read_b128 v[88:91], v238 offset:25344
	ds_read_b128 v[92:95], v237 offset:43776
	s_waitcnt lgkmcnt(6)
	v_mfma_f32_16x16x32_bf16 v[44:47], v[64:67], v[68:71], v[44:47]
	s_lshl_b32 s20, s20, 14
	v_lshl_add_u64 v[222:223], v[200:201], 0, s[20:21]
	v_add_co_u32_e32 v226, vcc, s38, v222
	s_waitcnt lgkmcnt(4)
	v_mfma_f32_16x16x32_bf16 v[40:43], v[64:67], v[76:79], v[40:43]
	v_addc_co_u32_e32 v227, vcc, 0, v223, vcc
	v_add_co_u32_e32 v224, vcc, s39, v222
	s_waitcnt lgkmcnt(2)
	v_mfma_f32_16x16x32_bf16 v[36:39], v[64:67], v[84:87], v[36:39]
	v_addc_co_u32_e32 v225, vcc, 0, v223, vcc
	v_add_co_u32_e32 v228, vcc, s40, v222
	s_waitcnt lgkmcnt(0)
	v_mfma_f32_16x16x32_bf16 v[32:35], v[64:67], v[92:95], v[32:35]
	v_addc_co_u32_e32 v229, vcc, 0, v223, vcc
	v_mfma_f32_16x16x32_bf16 v[28:31], v[72:75], v[68:71], v[28:31]
	v_mfma_f32_16x16x32_bf16 v[8:11], v[72:75], v[76:79], v[8:11]
	v_mfma_f32_16x16x32_bf16 v[4:7], v[72:75], v[84:87], v[4:7]
	v_mfma_f32_16x16x32_bf16 v[0:3], v[72:75], v[92:95], v[0:3]
	v_mfma_f32_16x16x32_bf16 v[16:19], v[80:83], v[68:71], v[16:19]
	v_mfma_f32_16x16x32_bf16 v[24:27], v[80:83], v[76:79], v[24:27]
	v_mfma_f32_16x16x32_bf16 v[20:23], v[80:83], v[84:87], v[20:23]
	v_mfma_f32_16x16x32_bf16 v[12:15], v[80:83], v[92:95], v[12:15]
	v_mfma_f32_16x16x32_bf16 v[64:67], v[88:91], v[68:71], v[56:59]
	v_mfma_f32_16x16x32_bf16 v[68:71], v[88:91], v[76:79], v[48:51]
	v_mfma_f32_16x16x32_bf16 v[72:75], v[88:91], v[84:87], v[60:63]
	v_mfma_f32_16x16x32_bf16 v[76:79], v[88:91], v[92:95], v[52:55]
	s_nop 0
	ds_read_b128 v[48:51], v238 offset:18496
	ds_read_b128 v[80:83], v237 offset:36928
	ds_read_b128 v[84:87], v238 offset:20800
	ds_read_b128 v[88:91], v237 offset:39232
	ds_read_b128 v[92:95], v238 offset:23104
	ds_read_b128 v[96:99], v237 offset:41536
	ds_read_b128 v[100:103], v238 offset:25408
	ds_read_b128 v[104:107], v237 offset:43840
	s_waitcnt lgkmcnt(0)
	s_barrier
; __device__ __forceinline__ uint2 pack4(f32x4 v) { return make_uint2(pack2(v[0], v[1]), pack2(v[2], v[3])); }
; __device__ __forceinline__ void phase_compress(const Params& p, u16* sm) {
;     ...
; #pragma unroll
;     for (int i = 0; i < 4; ++i) {
;       const int n = wn * 64 + i * 16 + fq * 4;
;       float bb[4] = {0.f, 0.f, 0.f, 0.f};
; #pragma unroll
;       for (int c8 = 0; c8 < 32; ++c8) {
;         const float4 bv = *(const float4*)(bias + c8 * 128 + n);
;         bb[0] += bv.x; bb[1] += bv.y; bb[2] += bv.z; bb[3] += bv.w;
;       }
; #pragma unroll
;       for (int j = 0; j < 4; ++j) {
;         const int rl = wm * 64 + j * 16 + fr;
;         f32x4 hv;
; #pragma unroll
;         for (int r = 0; r < 4; ++r) {
;           float xv = acc[i][j][r] + bb[r];
;           float inner = 0.7978845608028654f * (xv + 0.044715f * xv * xv * xv);
;           hv[r] = 0.5f * xv * (1.f + tanhf(inner));
;         }
;         *(uint2*)(sH + rl * 136 + n) = pack4(hv);
;       }
	v_mfma_f32_16x16x32_bf16 v[60:63], v[48:51], v[80:83], v[44:47]
	global_load_dwordx4 v[108:111], v[226:227], off offset:1536
	global_load_dwordx4 v[112:115], v[226:227], off offset:2048
	global_load_dwordx4 v[116:119], v[226:227], off offset:2560
	v_mfma_f32_16x16x32_bf16 v[44:47], v[84:87], v[80:83], v[28:31]
	global_load_dwordx4 v[120:123], v[226:227], off offset:3072
	global_load_dwordx4 v[124:127], v[226:227], off offset:3584
	global_load_dwordx4 v[128:131], v[224:225], off
	v_mfma_f32_16x16x32_bf16 v[28:31], v[92:95], v[80:83], v[16:19]
	global_load_dwordx4 v[132:135], v[224:225], off offset:512
	global_load_dwordx4 v[136:139], v[224:225], off offset:1024
	global_load_dwordx4 v[140:143], v[224:225], off offset:1536
	global_load_dwordx4 v[144:147], v[224:225], off offset:2048
	v_mfma_f32_16x16x32_bf16 v[16:19], v[92:95], v[104:107], v[12:15]
	global_load_dwordx4 v[148:151], v[224:225], off offset:2560
	global_load_dwordx4 v[152:155], v[224:225], off offset:3072
	global_load_dwordx4 v[156:159], v[224:225], off offset:3584
	v_mfma_f32_16x16x32_bf16 v[12:15], v[100:103], v[80:83], v[64:67]
	global_load_dwordx4 v[80:83], v[222:223], off offset:2048
	global_load_dwordx4 v[160:163], v[228:229], off
	global_load_dwordx4 v[164:167], v[228:229], off offset:512
	global_load_dwordx4 v[64:67], v[222:223], off
	v_mfma_f32_16x16x32_bf16 v[56:59], v[48:51], v[88:91], v[40:43]
	global_load_dwordx4 v[168:171], v[228:229], off offset:1024
	global_load_dwordx4 v[172:175], v[228:229], off offset:1536
	global_load_dwordx4 v[176:179], v[228:229], off offset:2048
	global_load_dwordx4 v[180:183], v[228:229], off offset:2560
	v_mfma_f32_16x16x32_bf16 v[40:43], v[84:87], v[88:91], v[8:11]
	global_load_dwordx4 v[184:187], v[228:229], off offset:3072
	global_load_dwordx4 v[188:191], v[228:229], off offset:3584
	v_mfma_f32_16x16x32_bf16 v[8:11], v[100:103], v[88:91], v[68:71]
	s_nop 2
	global_load_dwordx4 v[68:71], v[222:223], off offset:512
	v_mfma_f32_16x16x32_bf16 v[52:55], v[48:51], v[96:99], v[36:39]
	s_waitcnt vmcnt(7)
	v_add_f32_e32 v64, 0, v64
	v_mfma_f32_16x16x32_bf16 v[36:39], v[84:87], v[96:99], v[4:7]
	s_waitcnt vmcnt(0)
	v_add_f32_e32 v64, v64, v68
	v_mfma_f32_16x16x32_bf16 v[4:7], v[100:103], v[96:99], v[72:75]
	s_nop 2
	global_load_dwordx4 v[72:75], v[222:223], off offset:1024
	v_mfma_f32_16x16x32_bf16 v[48:51], v[48:51], v[104:107], v[32:35]
	v_mfma_f32_16x16x32_bf16 v[32:35], v[84:87], v[104:107], v[0:3]
	global_load_dwordx4 v[84:87], v[222:223], off offset:2560
	v_mfma_f32_16x16x32_bf16 v[0:3], v[100:103], v[104:107], v[76:79]
	global_load_dwordx4 v[100:103], v[226:227], off offset:512
	global_load_dwordx4 v[104:107], v[226:227], off offset:1024
	s_nop 0
	global_load_dwordx4 v[76:79], v[222:223], off offset:1536
	v_mfma_f32_16x16x32_bf16 v[24:27], v[92:95], v[88:91], v[24:27]
	global_load_dwordx4 v[88:91], v[222:223], off offset:3072
	s_waitcnt vmcnt(5)
	v_add_f32_e32 v64, v64, v72
	v_mfma_f32_16x16x32_bf16 v[20:23], v[92:95], v[96:99], v[20:23]
	global_load_dwordx4 v[92:95], v[222:223], off offset:3584
	global_load_dwordx4 v[96:99], v[224:225], off offset:-4096
	s_waitcnt vmcnt(3)
	v_add_f32_e32 v64, v64, v76
	v_add_f32_e32 v64, v64, v80
	v_add_f32_e32 v64, v64, v84
	s_waitcnt vmcnt(2)
	v_add_f32_e32 v64, v64, v88
	s_waitcnt vmcnt(1)
	v_add_f32_e32 v64, v64, v92
	s_waitcnt vmcnt(0)
	v_add_f32_e32 v64, v64, v96
	v_add_f32_e32 v64, v64, v100
	v_add_f32_e32 v64, v64, v104
	v_add_f32_e32 v64, v64, v108
	v_add_f32_e32 v64, v64, v112
	v_add_f32_e32 v64, v64, v116
	v_add_f32_e32 v64, v64, v120
	v_add_f32_e32 v64, v64, v124
	v_add_f32_e32 v64, v64, v128
	v_add_f32_e32 v64, v64, v132
	v_add_f32_e32 v64, v64, v136
	v_add_f32_e32 v64, v64, v140
	v_add_f32_e32 v64, v64, v144
	v_add_f32_e32 v64, v64, v148
	v_add_f32_e32 v64, v64, v152
	v_add_f32_e32 v64, v64, v156
	v_add_f32_e32 v64, v64, v160
	v_add_f32_e32 v64, v64, v164
	v_add_f32_e32 v64, v64, v168
	v_add_f32_e32 v64, v64, v172
	v_add_f32_e32 v64, v64, v176
	v_add_f32_e32 v64, v64, v180
	v_add_f32_e32 v64, v64, v184
	v_add_f32_e32 v64, v64, v188
	v_add_f32_e32 v68, v60, v64
	v_mul_f32_e32 v60, 0x3d372713, v68
	v_mul_f32_e32 v60, v68, v60
	v_fma_f32 v60, v68, v60, v68
	v_mul_f32_e32 v72, 0x3f4c422a, v60
	v_cmp_nlt_f32_e64 s[8:9], |v72|, s41
	s_and_saveexec_b64 s[26:27], s[8:9]
	s_xor_b64 s[8:9], exec, s[26:27]
	s_cbranch_execz .LBB0_899
	v_add_f32_e64 v60, |v72|, |v72|
	v_mul_f32_e32 v76, 0x3fb8aa3b, v60
	v_rndne_f32_e32 v80, v76
	v_sub_f32_e32 v84, v76, v80
	v_fma_f32 v76, v60, s42, -v76
	v_fmac_f32_e32 v76, 0x32a5705f, v60
	v_add_f32_e32 v76, v84, v76
	v_cvt_i32_f32_e32 v80, v80
	v_exp_f32_e32 v76, v76
	v_cmp_ngt_f32_e32 vcc, s43, v60
	v_ldexp_f32 v76, v76, v80
	s_nop 0
	v_cndmask_b32_e32 v76, 0, v76, vcc
	v_cmp_nlt_f32_e32 vcc, s44, v60
	s_nop 1
	v_cndmask_b32_e32 v60, v249, v76, vcc
	v_add_f32_e32 v60, 1.0, v60
	v_rcp_f32_e32 v60, v60
	s_nop 0
	v_fma_f32 v76, v60, -2.0, 1.0
